# diff-attn loop top: K-fragment LDS reads issued before the K/V tile write-back and next-tile loads
# speedup vs baseline: 1.0104x; 1.0104x over previous
; #define LAS __attribute__((address_space(3)))
; template <int NMAP, int VD, bool SWA> ...
;     ...
;     for (int i = 0; i < ntiles; ++i) {
;         const int t = ATT_TILE(i);
;         if (i + 1 < ntiles) { ATT_STORE((i + 1) & 1); if (i + 2 < ntiles) ATT_LOAD(ATT_TILE(i + 2)); }
;         const LAS bf16_t* kS = (const LAS bf16_t*)(lds + (i & 1) * BUFB);
;         const LAS bf16_t* vS = (const LAS bf16_t*)(lds + (i & 1) * BUFB + KBYTES);
;         bf16x8 pf[NMAP][2];
;         f32x4 sacc[NMAP][4];
; #pragma unroll
;         for (int mp = 0; mp < NMAP; ++mp) {
;             bf16x8 kf[4][2];
; #pragma unroll
;             for (int kt = 0; kt < 4; ++kt)
; #pragma unroll
;                 for (int ks = 0; ks < 2; ++ks) kf[kt][ks] = *(const LAS bf16x8*)(kS + (16 * kt + fr) * KP + mp * KMS + ks * 32 + fq * 8);
;             __builtin_amdgcn_sched_barrier(0);
; #pragma unroll
;             for (int kt = 0; kt < 4; ++kt) sacc[mp][kt] = __builtin_amdgcn_mfma_f32_16x16x32_bf16(kf[kt][0], qf[mp][0], negm[mp], 0, 0, 0);
; #pragma unroll
;             for (int kt = 0; kt < 4; ++kt) sacc[mp][kt] = __builtin_amdgcn_mfma_f32_16x16x32_bf16(kf[kt][1], qf[mp][1], sacc[mp][kt], 0, 0, 0);
;         }
;         bf16x8 va[4];
;     ...
; #pragma unroll
;         for (int i2 = 0; i2 < 4; ++i2) ATT_LDV(va[i2], i2);
;         if (SWA && t >= 4) {
;             const int dq = qp0 + 16 * w + fr - (64 * (t - 4) + 4 * fq);
; #pragma unroll
;             for (int kt = 0; kt < 4; ++kt)
; #pragma unroll
;                 for (int r = 0; r < 4; ++r) { const int d = dq - 16 * kt - r; if (d > 128 || d < -128) {
; #pragma unroll
;                     for (int mp = 0; mp < NMAP; ++mp) sacc[mp][kt][r] = -INFINITY; } }
;         }
;         float mx[NMAP];
; #pragma unroll
;         for (int mp = 0; mp < NMAP; ++mp) {
;             float v = fmax2(fmax2(sacc[mp][0][0], sacc[mp][0][1]), fmax2(sacc[mp][0][2], sacc[mp][0][3]));
; #pragma unroll
;             for (int kt = 1; kt < 4; ++kt) v = fmax2(v, fmax2(fmax2(sacc[mp][kt][0], sacc[mp][kt][1]), fmax2(sacc[mp][kt][2], sacc[mp][kt][3])));
;             mx[mp] = v;
;         }
; #pragma unroll
;         for (int mp = 0; mp < NMAP; ++mp) mx[mp] = fmax2(mx[mp], __shfl_xor(mx[mp], 16));
; #pragma unroll
;         for (int mp = 0; mp < NMAP; ++mp) mx[mp] = fmax2(mx[mp], __shfl_xor(mx[mp], 32));
; #pragma unroll
;         for (int mp = 0; mp < NMAP; ++mp) {
.LBB0_125:
	s_mov_b32 s15, s3
	s_add_i32 s3, s3, 1
	s_bitcmp1_b32 s15, 0
	s_cselect_b32 s15, 0x9000, 0
	v_add3_u32 v138, s15, v183, v182
	ds_read_b128 v[58:61], v138
	ds_read_b128 v[94:97], v138 offset:64
	ds_read_b128 v[114:117], v138 offset:4608
	ds_read_b128 v[118:121], v138 offset:4672
	ds_read_b128 v[122:125], v138 offset:9216
	ds_read_b128 v[126:129], v138 offset:9280
	ds_read_b128 v[130:133], v138 offset:13824
	ds_read_b128 v[134:137], v138 offset:13888
	s_bitcmp1_b32 s3, 0
	s_cselect_b32 s14, 0x9000, 0
	v_add3_u32 v240, s14, v208, v209
	v_add3_u32 v241, s14, v210, v211
	s_waitcnt vmcnt(0)
	ds_write_b128 v240, v[86:89]
	ds_write_b128 v241, v[90:93]
	ds_write_b128 v240, v[98:101] offset:18432
	ds_write_b128 v241, v[102:105] offset:18432
	global_load_dwordx4 v[86:89], v236, s[34:35]
	global_load_dwordx4 v[90:93], v237, s[34:35]
	global_load_dwordx4 v[98:101], v238, s[34:35]
	global_load_dwordx4 v[102:105], v239, s[34:35]
	s_add_u32 s34, s34, 0x4000
	s_addc_u32 s35, s35, 0
	s_waitcnt lgkmcnt(5)
	v_mfma_f32_16x16x32_bf16 v[58:61], v[58:61], v[14:17], v[106:109]
	v_mfma_f32_16x16x32_bf16 v[114:117], v[114:117], v[14:17], v[106:109]
	v_mfma_f32_16x16x32_bf16 v[122:125], v[122:125], v[14:17], v[106:109]
	v_mfma_f32_16x16x32_bf16 v[130:133], v[130:133], v[14:17], v[106:109]
	v_mfma_f32_16x16x32_bf16 v[154:157], v[94:97], v[10:13], v[58:61]
	v_mfma_f32_16x16x32_bf16 v[150:153], v[118:121], v[10:13], v[114:117]
	v_mfma_f32_16x16x32_bf16 v[146:149], v[126:129], v[10:13], v[122:125]
	s_waitcnt lgkmcnt(4)
	v_mfma_f32_16x16x32_bf16 v[94:97], v[134:137], v[10:13], v[130:133]
	ds_read_b128 v[58:61], v138 offset:128
	ds_read_b128 v[114:117], v138 offset:192
	ds_read_b128 v[118:121], v138 offset:4736
	ds_read_b128 v[122:125], v138 offset:4800
	ds_read_b128 v[126:129], v138 offset:9344
	ds_read_b128 v[130:133], v138 offset:9408
	ds_read_b128 v[134:137], v138 offset:13952
	ds_read_b128 v[212:215], v138 offset:14016
	s_waitcnt lgkmcnt(1)
	v_mfma_f32_16x16x32_bf16 v[58:61], v[58:61], v[6:9], v[110:113]
	v_mfma_f32_16x16x32_bf16 v[118:121], v[118:121], v[6:9], v[110:113]
	v_mfma_f32_16x16x32_bf16 v[142:145], v[114:117], v[2:5], v[58:61]
	v_max3_f32 v235, v154, v155, v156
	v_max3_f32 v235, v235, v157, v150
	v_max3_f32 v235, v235, v151, v152
	v_mfma_f32_16x16x32_bf16 v[126:129], v[126:129], v[6:9], v[110:113]
	v_max3_f32 v235, v235, v153, v146
	v_max3_f32 v235, v235, v147, v148
	v_mfma_f32_16x16x32_bf16 v[134:137], v[134:137], v[6:9], v[110:113]
	v_max3_f32 v235, v235, v149, v94
	v_max3_f32 v235, v235, v95, v96
	v_mfma_f32_16x16x32_bf16 v[138:141], v[122:125], v[2:5], v[118:121]
	v_max_f32_e32 v235, v235, v97
	v_mfma_f32_16x16x32_bf16 v[118:121], v[130:133], v[2:5], v[126:129]
	v_max3_f32 v59, v142, v143, v144
	s_waitcnt lgkmcnt(0)
	v_mfma_f32_16x16x32_bf16 v[114:117], v[212:215], v[2:5], v[134:137]
	v_add3_u32 v212, s15, v0, v181
	ds_read_b64_tr_b16 v[134:135], v212 offset:18432
	ds_read_b64_tr_b16 v[130:131], v212 offset:18464
	ds_read_b64_tr_b16 v[136:137], v212 offset:23040
	ds_read_b64_tr_b16 v[132:133], v212 offset:23072
	ds_read_b64_tr_b16 v[126:127], v212 offset:18496
	ds_read_b64_tr_b16 v[128:129], v212 offset:23104
	ds_read_b64_tr_b16 v[122:123], v212 offset:18528
	ds_read_b64_tr_b16 v[124:125], v212 offset:23136
	v_max3_f32 v59, v59, v145, v138
	v_max3_f32 v59, v59, v139, v140
	v_max3_f32 v59, v59, v141, v118
	v_max3_f32 v59, v59, v119, v120
	v_max3_f32 v59, v59, v121, v114
	v_max3_f32 v59, v59, v115, v116
	v_max_f32_e32 v225, v59, v117
	v_cmp_lt_f32_e32 vcc, s72, v235
	s_cbranch_vccz .LBB0_127
	ds_bpermute_b32 v60, v179, v235
	s_waitcnt lgkmcnt(0)
	v_max_f32_e32 v58, v235, v60
	ds_bpermute_b32 v60, v180, v58
	s_waitcnt lgkmcnt(0)
	v_max_f32_e32 v58, v58, v60
	v_max_f32_e32 v58, v58, v58
	v_max_f32_e32 v61, 0, v58
	v_exp_f32_e64 v60, -v61
	v_sub_f32_e32 v154, v154, v61
	v_sub_f32_e32 v155, v155, v61
	v_sub_f32_e32 v156, v156, v61
	v_pk_add_f32 v[58:59], v[166:167], v[60:61]
	v_pk_mul_f32 v[166:167], v[166:167], v[60:61]
	v_xor_b32_e32 v58, 0x80000000, v59
	v_mov_b32_e32 v167, v59
	v_sub_f32_e32 v157, v157, v61
	v_sub_f32_e32 v150, v150, v61
	v_sub_f32_e32 v151, v151, v61
	v_sub_f32_e32 v152, v152, v61
	v_sub_f32_e32 v153, v153, v61
	v_sub_f32_e32 v146, v146, v61
	v_sub_f32_e32 v147, v147, v61
	v_sub_f32_e32 v148, v148, v61
	v_sub_f32_e32 v149, v149, v61
	v_sub_f32_e32 v94, v94, v61
	v_sub_f32_e32 v95, v95, v61
	v_sub_f32_e32 v96, v96, v61
	v_sub_f32_e32 v97, v97, v61
	v_pk_mul_f32 v[80:81], v[80:81], v[60:61] op_sel_hi:[1,0]
	v_pk_mul_f32 v[78:79], v[78:79], v[60:61] op_sel_hi:[1,0]
	v_pk_mul_f32 v[76:77], v[76:77], v[60:61] op_sel_hi:[1,0]
	v_pk_mul_f32 v[74:75], v[74:75], v[60:61] op_sel_hi:[1,0]
	v_pk_mul_f32 v[68:69], v[68:69], v[60:61] op_sel_hi:[1,0]
	v_pk_mul_f32 v[66:67], v[66:67], v[60:61] op_sel_hi:[1,0]
	v_pk_mul_f32 v[56:57], v[56:57], v[60:61] op_sel_hi:[1,0]
	v_pk_mul_f32 v[54:55], v[54:55], v[60:61] op_sel_hi:[1,0]
	v_pk_mul_f32 v[48:49], v[48:49], v[60:61] op_sel_hi:[1,0]
	v_pk_mul_f32 v[46:47], v[46:47], v[60:61] op_sel_hi:[1,0]
	v_pk_mul_f32 v[40:41], v[40:41], v[60:61] op_sel_hi:[1,0]
	v_pk_mul_f32 v[38:39], v[38:39], v[60:61] op_sel_hi:[1,0]
	v_pk_mul_f32 v[32:33], v[32:33], v[60:61] op_sel_hi:[1,0]
	v_pk_mul_f32 v[30:31], v[30:31], v[60:61] op_sel_hi:[1,0]
	v_pk_mul_f32 v[24:25], v[24:25], v[60:61] op_sel_hi:[1,0]
	v_pk_mul_f32 v[22:23], v[22:23], v[60:61] op_sel_hi:[1,0]
	v_mov_b32_e32 v59, v58
	v_mov_b32_e32 v60, v58
	v_mov_b32_e32 v61, v58
	v_mov_b32_e32 v106, v58
	v_mov_b32_e32 v107, v58
	v_mov_b32_e32 v108, v58
	v_mov_b32_e32 v109, v58
	s_branch .LBB0_128
